# P5: the wr=0 half's re-alignment barrier moved from before the epilogue to after its set-up + rstd scaling, so that work overlaps the other half's last MFMA segment; on top of v44
# baseline (speedup 1.0000x reference)
; #define PG8_BAR __builtin_amdgcn_s_barrier()
; template <class Epi, class Sched>
; __device__ __forceinline__ void gemm_phase(LAS unsigned char* lds, const Gemm g, const Sched& S, const Epi& E) {
;     ...
;         if (wr == 0) PG8_BAR;
;     __device__ __forceinline__ void operator()(AccT& acc, const Unit& u, int wr, int wc, int fr, int fq) const {
;         const int b = u.pm >> 6, tstart = (u.pm & 63) * 256;
;         const long arow0 = (long)u.pm * 256;
;         const int colg0 = u.pn * 128 + wc * 32 + fq * 8;
;         f32x4 cwg[2][3], cwv[2][3], cbg[2], cbv[2];
; #pragma unroll
;         for (int n = 0; n < 1; ++n) { const int colg = colg0 + n * 4, colv = FF + colg;
; #pragma unroll
;             for (int j = 0; j < 3; ++j) { cwg[n][j] = *(const f32x4*)(cw + j * FF2 + colg); cwv[n][j] = *(const f32x4*)(cw + j * FF2 + colv); }
;             cbg[n] = *(const f32x4*)(cb + colg); cbv[n] = *(const f32x4*)(cb + colv); }
;         float sq[2][4];
; #pragma unroll
;         for (int ai = 0; ai < 2; ++ai)
; #pragma unroll
;             for (int m = 0; m < 4; ++m) { const int rl = ai * 128 + wr * 64 + m * 16 + fr, t = tstart + rl; sq[ai][m] = ssq[arow0 + rl]; }
; #pragma unroll
;         for (int ai = 0; ai < 2; ++ai)
; #pragma unroll
;             for (int m = 0; m < 4; ++m) {
;                 const int rl = ai * 128 + wr * 64 + m * 16 + fr;
;                 const int t = tstart + rl;
;                 const float rs = __builtin_amdgcn_rsqf(sq[ai][m] * (1.0f / 1024.0f) + EPS);
; #pragma unroll
;                 for (int bj = 0; bj < 2; ++bj)
; #pragma unroll
;                     for (int n = 0; n < 2; ++n) acc[ai][bj][m][n] = acc[ai][bj][m][n] * rs;
;             }
.LBB0_1028:
	s_lshl_b32 s3, s22, 7
	v_readlane_b32 s9, v246, 38
	s_ashr_i32 s17, s16, 31
	v_readlane_b32 s18, v246, 20
	v_readlane_b32 s19, v246, 21
	v_readlane_b32 s20, v246, 30
	s_or_b32 s3, s3, s9
	v_lshlrev_b32_e32 v182, 3, v230
	v_mov_b32_e32 v183, 0
	v_mov_b32_e32 v193, 0
	v_add_u32_e32 v182, s3, v182
	s_lshl_b64 s[14:15], s[16:17], 10
	v_lshl_add_u32 v192, v229, 2, s20
	s_add_u32 s14, s18, s14
	s_addc_u32 s15, s19, s15
	v_cmp_eq_u32_e64 s[48:49], 0, v229
	v_cmp_eq_u32_e64 s[50:51], 15, v229
	s_cmp_eq_u32 s20, 0
	s_cselect_b64 s[54:55], -1, 0
	s_cselect_b64 s[72:73], 0, -1
	s_mov_b64 s[52:53], 0x2000
	s_and_b64 s[74:75], s[48:49], s[54:55]
	s_and_b64 s[76:77], s[50:51], s[72:73]
	s_and_b64 s[80:81], s[48:49], s[72:73]
	s_lshl_b64 s[16:17], s[16:17], 8
	v_lshl_add_u64 v[184:185], s[16:17], 0, v[192:193]
	v_mov_b64_e32 v[216:217], s[84:85]
	s_movk_i32 s3, 0x1600
	v_mad_u64_u32 v[216:217], s[22:23], v184, s3, v[216:217]
	v_mad_i32_i24 v217, v185, s3, v217
	v_lshl_add_u64 v[184:185], v[182:183], 1, v[216:217]
	s_mov_b32 s56, 0
	s_mov_b32 s57, 0
	s_mov_b32 s58, 5632
	s_mov_b32 s59, 0
	s_mov_b32 s60, 11264
	s_mov_b32 s61, 0
	s_mov_b32 s62, 16896
	s_mov_b32 s63, 0
	s_mov_b32 s64, 720896
	s_mov_b32 s65, 0
	s_mov_b32 s66, 726528
	s_mov_b32 s67, 0
	s_mov_b32 s68, 732160
	s_mov_b32 s69, 0
	s_mov_b32 s70, 737792
	s_mov_b32 s71, 0
	s_lshl_b32 s3, s20, 5
	s_lshl_b32 s9, s9, 4
	s_add_i32 s3, s3, s9
	s_add_i32 s3, s3, 0x20000
	v_lshl_add_u32 v189, v230, 7, s3
	s_lshl_b32 s9, s9, 1
	s_add_i32 s9, s9, 0x22000
	v_lshl_add_u32 v255, v230, 8, s9
	v_lshl_add_u32 v254, v229, 4, v255
	ds_write_b128 v254, v[250:253]
	s_nop 1
	v_add_u32_e32 v188, 0xfffff800, v189
	v_mov_b32_e32 v186, 0xbf3a00e3
	v_fmamk_f32 v126, v194, 0x3a800000, v223
	v_rsq_f32_e32 v126, v126
	s_nop 0
	v_pk_mul_f32 v[160:161], v[160:161], v[126:127] op_sel_hi:[1,0]
	v_pk_mul_f32 v[162:163], v[162:163], v[126:127] op_sel_hi:[1,0]
	v_pk_mul_f32 v[60:61], v[60:61], v[126:127] op_sel_hi:[1,0]
	v_pk_mul_f32 v[62:63], v[62:63], v[126:127] op_sel_hi:[1,0]
	v_pk_mul_f32 v[156:157], v[156:157], v[126:127] op_sel_hi:[1,0]
	v_pk_mul_f32 v[158:159], v[158:159], v[126:127] op_sel_hi:[1,0]
	v_pk_mul_f32 v[56:57], v[56:57], v[126:127] op_sel_hi:[1,0]
	v_pk_mul_f32 v[58:59], v[58:59], v[126:127] op_sel_hi:[1,0]
	v_fmamk_f32 v126, v195, 0x3a800000, v223
	v_rsq_f32_e32 v126, v126
	s_nop 0
	v_pk_mul_f32 v[144:145], v[144:145], v[126:127] op_sel_hi:[1,0]
	v_pk_mul_f32 v[146:147], v[146:147], v[126:127] op_sel_hi:[1,0]
	v_pk_mul_f32 v[52:53], v[52:53], v[126:127] op_sel_hi:[1,0]
	v_pk_mul_f32 v[54:55], v[54:55], v[126:127] op_sel_hi:[1,0]
	v_pk_mul_f32 v[118:119], v[118:119], v[126:127] op_sel_hi:[1,0]
	v_pk_mul_f32 v[120:121], v[120:121], v[126:127] op_sel_hi:[1,0]
	v_pk_mul_f32 v[40:41], v[40:41], v[126:127] op_sel_hi:[1,0]
	v_pk_mul_f32 v[42:43], v[42:43], v[126:127] op_sel_hi:[1,0]
	v_fmamk_f32 v126, v196, 0x3a800000, v223
	v_rsq_f32_e32 v126, v126
	s_nop 0
	v_pk_mul_f32 v[140:141], v[140:141], v[126:127] op_sel_hi:[1,0]
	v_pk_mul_f32 v[142:143], v[142:143], v[126:127] op_sel_hi:[1,0]
	v_pk_mul_f32 v[36:37], v[36:37], v[126:127] op_sel_hi:[1,0]
	v_pk_mul_f32 v[38:39], v[38:39], v[126:127] op_sel_hi:[1,0]
	v_pk_mul_f32 v[114:115], v[114:115], v[126:127] op_sel_hi:[1,0]
	v_pk_mul_f32 v[116:117], v[116:117], v[126:127] op_sel_hi:[1,0]
	v_pk_mul_f32 v[32:33], v[32:33], v[126:127] op_sel_hi:[1,0]
	v_pk_mul_f32 v[34:35], v[34:35], v[126:127] op_sel_hi:[1,0]
	v_fmamk_f32 v126, v197, 0x3a800000, v223
	v_rsq_f32_e32 v126, v126
	s_nop 0
	v_pk_mul_f32 v[152:153], v[152:153], v[126:127] op_sel_hi:[1,0]
	v_pk_mul_f32 v[154:155], v[154:155], v[126:127] op_sel_hi:[1,0]
	v_pk_mul_f32 v[48:49], v[48:49], v[126:127] op_sel_hi:[1,0]
	v_pk_mul_f32 v[50:51], v[50:51], v[126:127] op_sel_hi:[1,0]
	v_pk_mul_f32 v[148:149], v[148:149], v[126:127] op_sel_hi:[1,0]
	v_pk_mul_f32 v[150:151], v[150:151], v[126:127] op_sel_hi:[1,0]
	v_pk_mul_f32 v[44:45], v[44:45], v[126:127] op_sel_hi:[1,0]
	v_pk_mul_f32 v[46:47], v[46:47], v[126:127] op_sel_hi:[1,0]
	v_fmamk_f32 v126, v198, 0x3a800000, v223
	v_rsq_f32_e32 v126, v126
	s_nop 0
	v_pk_mul_f32 v[136:137], v[136:137], v[126:127] op_sel_hi:[1,0]
	v_pk_mul_f32 v[138:139], v[138:139], v[126:127] op_sel_hi:[1,0]
	v_pk_mul_f32 v[28:29], v[28:29], v[126:127] op_sel_hi:[1,0]
	v_pk_mul_f32 v[30:31], v[30:31], v[126:127] op_sel_hi:[1,0]
	v_pk_mul_f32 v[132:133], v[132:133], v[126:127] op_sel_hi:[1,0]
	v_pk_mul_f32 v[134:135], v[134:135], v[126:127] op_sel_hi:[1,0]
	v_pk_mul_f32 v[24:25], v[24:25], v[126:127] op_sel_hi:[1,0]
	v_pk_mul_f32 v[26:27], v[26:27], v[126:127] op_sel_hi:[1,0]
	v_fmamk_f32 v126, v199, 0x3a800000, v223
	v_rsq_f32_e32 v126, v126
	s_nop 0
	v_pk_mul_f32 v[76:77], v[76:77], v[126:127] op_sel_hi:[1,0]
	v_pk_mul_f32 v[78:79], v[78:79], v[126:127] op_sel_hi:[1,0]
	v_pk_mul_f32 v[12:13], v[12:13], v[126:127] op_sel_hi:[1,0]
	v_pk_mul_f32 v[14:15], v[14:15], v[126:127] op_sel_hi:[1,0]
	v_pk_mul_f32 v[72:73], v[72:73], v[126:127] op_sel_hi:[1,0]
	v_pk_mul_f32 v[74:75], v[74:75], v[126:127] op_sel_hi:[1,0]
	v_pk_mul_f32 v[8:9], v[8:9], v[126:127] op_sel_hi:[1,0]
	v_pk_mul_f32 v[10:11], v[10:11], v[126:127] op_sel_hi:[1,0]
	v_fmamk_f32 v126, v200, 0x3a800000, v223
	v_rsq_f32_e32 v126, v126
	s_nop 0
	v_pk_mul_f32 v[68:69], v[68:69], v[126:127] op_sel_hi:[1,0]
	v_pk_mul_f32 v[70:71], v[70:71], v[126:127] op_sel_hi:[1,0]
	v_pk_mul_f32 v[4:5], v[4:5], v[126:127] op_sel_hi:[1,0]
	v_pk_mul_f32 v[6:7], v[6:7], v[126:127] op_sel_hi:[1,0]
	v_pk_mul_f32 v[64:65], v[64:65], v[126:127] op_sel_hi:[1,0]
	v_pk_mul_f32 v[66:67], v[66:67], v[126:127] op_sel_hi:[1,0]
	v_pk_mul_f32 v[0:1], v[0:1], v[126:127] op_sel_hi:[1,0]
	v_pk_mul_f32 v[2:3], v[2:3], v[126:127] op_sel_hi:[1,0]
	v_fmamk_f32 v126, v201, 0x3a800000, v223
	v_rsq_f32_e32 v126, v126
	s_nop 0
	v_pk_mul_f32 v[122:123], v[122:123], v[126:127] op_sel_hi:[1,0]
	v_pk_mul_f32 v[124:125], v[124:125], v[126:127] op_sel_hi:[1,0]
	v_pk_mul_f32 v[16:17], v[16:17], v[126:127] op_sel_hi:[1,0]
	v_pk_mul_f32 v[18:19], v[18:19], v[126:127] op_sel_hi:[1,0]
	v_pk_mul_f32 v[128:129], v[128:129], v[126:127] op_sel_hi:[1,0]
	v_pk_mul_f32 v[130:131], v[130:131], v[126:127] op_sel_hi:[1,0]
	v_pk_mul_f32 v[20:21], v[20:21], v[126:127] op_sel_hi:[1,0]
	v_pk_mul_f32 v[22:23], v[22:23], v[126:127] op_sel_hi:[1,0]
	v_mov_b64_e32 v[194:195], 0x200
	v_mov_b64_e32 v[196:197], 0x680
	v_mov_b64_e32 v[198:199], 0x67f
	v_mov_b64_e32 v[200:201], 0x1ff
	s_cmp_eq_u32 s20, 0
	s_cbranch_scc0 .Lmy_p5_nb
	s_barrier
; #define LAS __attribute__((address_space(3)))
;     __device__ __forceinline__ void operator()(AccT& acc, const Unit& u, int wr, int wc, int fr, int fq) const {
;     ...
;         if (fr >= 14) {
; #pragma unroll
;             for (int ai = 0; ai < 2; ++ai)
; #pragma unroll
;                 for (int bj = 0; bj < 2; ++bj)
; #pragma unroll
;                     for (int n = 0; n < 2; ++n)
;                         *(LAS f32x4*)(xch + (((ai * 2 + wr) * 2 + (fr - 14)) * 256 + bj * 128 + wc * 32 + fq * 8 + n * 4)) = acc[ai][bj][3][n];
;         }
;         asm volatile("s_waitcnt lgkmcnt(0)" ::: "memory"); __builtin_amdgcn_s_barrier(); asm volatile("" ::: "memory");
.Lmy_p5_nb:
	s_and_saveexec_b64 s[20:21], s[50:51]
	s_cbranch_execz .Lmy_p5_xw
	ds_write_b128 v189, v[140:143]
	ds_write_b128 v189, v[114:117] offset:16
	ds_write_b128 v189, v[36:39] offset:32
	ds_write_b128 v189, v[32:35] offset:48
	ds_write_b128 v189, v[152:155] offset:64
	ds_write_b128 v189, v[148:151] offset:80
	ds_write_b128 v189, v[48:51] offset:96
	ds_write_b128 v189, v[44:47] offset:112
	ds_write_b128 v189, v[68:71] offset:4096
	ds_write_b128 v189, v[64:67] offset:4112
	ds_write_b128 v189, v[4:7] offset:4128
	ds_write_b128 v189, v[0:3] offset:4144
	ds_write_b128 v189, v[122:125] offset:4160
	ds_write_b128 v189, v[128:131] offset:4176
	ds_write_b128 v189, v[16:19] offset:4192
	ds_write_b128 v189, v[20:23] offset:4208
